# nt on x loads plus nt on the other wide contiguous single-use streams (hpost inputs, final-norm loads/stores, wave-7 p rows)
# speedup vs baseline: 1.0135x; 1.0135x over previous
.LBB0_384:
	s_or_b64 exec, exec, s[68:69]
	s_lshr_b32 s75, s74, 6
	s_cmpk_gt_u32 s74, 0xff
	s_mov_b64 s[0:1], -1
	s_cbranch_scc0 .LBB0_396
	s_setprio 1
	s_and_b32 s0, s94, 15
	s_lshl_b32 s72, s0, 22
	s_add_i32 s73, s75, -4
	s_cmp_lg_u32 s73, 0
	s_cselect_b64 s[0:1], -1, 0
	s_cmpk_lt_u32 s74, 0x1c0
	s_cselect_b64 s[68:69], -1, 0
	s_not_b32 s70, s75
	s_lshl_b32 s70, s70, 5
	s_and_b32 s87, s70, 32
	s_add_i32 s70, s75, -5
	v_or_b32_e32 v2, s87, v83
	s_cmp_lt_u32 s70, 2
	v_mul_u32_u24_e32 v3, 0x110, v2
	s_cselect_b64 s[70:71], -1, 0
	v_mul_u32_u24_e32 v105, 0x50, v2
	v_lshl_add_u32 v106, s73, 7, v90
	v_lshl_or_b32 v2, s73, 5, v83
	v_lshl_add_u32 v108, s73, 6, v91
	s_add_i32 s73, s87, s95
	s_waitcnt lgkmcnt(0)
	s_barrier
	s_add_i32 s73, s73, s86
	s_waitcnt lgkmcnt(0)
	s_barrier
	s_movk_i32 s88, 0x50
	s_lshl_b32 s73, s73, 1
	v_mul_lo_u32 v107, v2, s88
	s_or_b32 s72, s72, s73
	s_mov_b32 s73, s96
	v_mov_b32_e32 v2, 0
	s_mov_b32 s87, 1
	v_lshl_add_u64 v[80:81], v[78:79], 0, s[72:73]
	v_add_u32_e32 v109, v86, v3
	v_mov_b32_e32 v3, v2
	v_mov_b32_e32 v4, v2
	v_mov_b32_e32 v5, v2
	s_waitcnt vmcnt(0)
	v_mov_b32_e32 v6, v2
	v_mov_b32_e32 v7, v2
	v_mov_b32_e32 v8, v2
	v_mov_b32_e32 v9, v2
	v_mov_b32_e32 v10, v2
	v_mov_b32_e32 v11, v2
	v_mov_b32_e32 v12, v2
	v_mov_b32_e32 v13, v2
	v_mov_b32_e32 v14, v2
	v_mov_b32_e32 v15, v2
	v_mov_b32_e32 v16, v2
	v_mov_b32_e32 v17, v2
	v_mov_b32_e32 v18, v2
	v_mov_b32_e32 v19, v2
	v_mov_b32_e32 v20, v2
	v_mov_b32_e32 v21, v2
	v_mov_b32_e32 v22, v2
	v_mov_b32_e32 v23, v2
	v_mov_b32_e32 v24, v2
	v_mov_b32_e32 v25, v2
	v_mov_b32_e32 v26, v2
	v_mov_b32_e32 v27, v2
	v_mov_b32_e32 v28, v2
	v_mov_b32_e32 v29, v2
	v_mov_b32_e32 v30, v2
	v_mov_b32_e32 v31, v2
	v_mov_b32_e32 v32, v2
	v_mov_b32_e32 v33, v2
	s_and_b64 vcc, exec, s[68:69]
	s_cbranch_vccnz .Lmy_pc0_nosetup
	v_readlane_b32 s98, v255, 3
	v_readlane_b32 s99, v255, 4
	v_readlane_b32 s100, v255, 17
	s_nop 3
	s_lshl_b32 s101, s100, 18
	s_add_u32 s98, s98, s101
	s_addc_u32 s99, s99, 0
	v_lshlrev_b32_e32 v232, 4, v158
	v_mov_b32_e32 v233, 0
	v_lshl_add_u64 v[232:233], s[98:99], 0, v[232:233]
	s_lshl_b32 s101, s100, 17
	s_add_u32 s98, s80, s101
	s_addc_u32 s99, s81, 0
	s_add_u32 s98, s98, 0x34000000
	s_addc_u32 s99, s99, 0
	v_lshlrev_b32_e32 v234, 3, v158
	v_mov_b32_e32 v235, 0
	v_lshl_add_u64 v[234:235], s[98:99], 0, v[234:235]
	v_mov_b32_e32 v236, 0x800
	v_mov_b32_e32 v237, 0
	v_mov_b32_e32 v238, 0x400
	v_mov_b32_e32 v239, 0
	v_mov_b32_e32 v244, 0x100
	v_mov_b32_e32 v245, 0
	v_mov_b32_e32 v202, 0x1000
	v_mov_b32_e32 v203, 0
	v_mov_b32_e32 v195, 0
	global_load_dwordx4 v[224:227], v[232:233], off nt
	global_load_dwordx4 v[228:231], v[232:233], off offset:1024 nt
	v_lshl_add_u64 v[232:233], v[232:233], 0, v[236:237]

.Lmy_tw0_done:
	s_cmpk_eq_i32 s87, 0x80
	s_cbranch_scc1 .LBB0_392
	global_load_dwordx4 v[224:227], v[232:233], off nt
	global_load_dwordx4 v[228:231], v[232:233], off offset:1024 nt
	v_lshl_add_u64 v[232:233], v[232:233], 0, v[236:237]
	s_branch .LBB0_392

.LBB0_415:
	s_or_b64 exec, exec, s[68:69]
	v_readfirstlane_b32 s88, v0
	s_lshl_b32 s0, s94, 12
	s_lshr_b32 s87, s88, 6
	s_cmpk_gt_u32 s88, 0xff
	s_mov_b64 s[68:69], -1
	s_cbranch_scc0 .LBB0_427
	s_setprio 1
	s_mov_b32 s1, s96
	s_lshl_b64 s[74:75], s[0:1], 10
	s_add_i32 s92, s87, -4
	s_cmp_lg_u32 s92, 0
	s_cselect_b64 s[68:69], -1, 0
	s_cmpk_lt_u32 s88, 0x1c0
	s_cselect_b64 s[70:71], -1, 0
	s_not_b32 s72, s87
	s_lshl_b32 s72, s72, 5
	s_and_b32 s93, s72, 32
	s_add_i32 s72, s87, -5
	v_or_b32_e32 v2, s93, v83
	s_cmp_lt_u32 s72, 2
	v_mul_u32_u24_e32 v3, 0x110, v2
	s_cselect_b64 s[72:73], -1, 0
	v_mul_u32_u24_e32 v105, 0x50, v2
	v_lshl_add_u32 v106, s92, 7, v90
	v_lshl_or_b32 v2, s92, 5, v83
	v_lshl_add_u32 v108, s92, 6, v91
	s_add_i32 s92, s93, s95
	s_add_i32 s92, s92, s86
	s_waitcnt lgkmcnt(0)
	s_barrier
	s_lshl_b32 s86, s92, 1
	s_waitcnt lgkmcnt(0)
	s_barrier
	s_movk_i32 vcc_lo, 0x50
	s_add_u32 s74, s74, s86
	v_mul_lo_u32 v107, v2, vcc_lo
	s_addc_u32 s75, s75, 0
	v_mov_b32_e32 v2, 0
	s_mov_b32 s1, 0
	v_lshl_add_u64 v[80:81], v[76:77], 0, s[74:75]
	s_mov_b64 s[74:75], 0
	v_add_u32_e32 v109, v86, v3
	v_mov_b32_e32 v3, v2
	v_mov_b32_e32 v4, v2
	v_mov_b32_e32 v5, v2
	s_waitcnt vmcnt(0)
	v_mov_b32_e32 v6, v2
	v_mov_b32_e32 v7, v2
	v_mov_b32_e32 v8, v2
	v_mov_b32_e32 v9, v2
	v_mov_b32_e32 v10, v2
	v_mov_b32_e32 v11, v2
	v_mov_b32_e32 v12, v2
	v_mov_b32_e32 v13, v2
	v_mov_b32_e32 v14, v2
	v_mov_b32_e32 v15, v2
	v_mov_b32_e32 v16, v2
	v_mov_b32_e32 v17, v2
	v_mov_b32_e32 v18, v2
	v_mov_b32_e32 v19, v2
	v_mov_b32_e32 v20, v2
	v_mov_b32_e32 v21, v2
	v_mov_b32_e32 v22, v2
	v_mov_b32_e32 v23, v2
	v_mov_b32_e32 v24, v2
	v_mov_b32_e32 v25, v2
	v_mov_b32_e32 v26, v2
	v_mov_b32_e32 v27, v2
	v_mov_b32_e32 v28, v2
	v_mov_b32_e32 v29, v2
	v_mov_b32_e32 v30, v2
	v_mov_b32_e32 v31, v2
	v_mov_b32_e32 v32, v2
	v_mov_b32_e32 v33, v2
	s_and_b64 vcc, exec, s[70:71]
	s_cbranch_vccnz .Lmy_pc1_nosetup
	v_readlane_b32 s98, v255, 3
	v_readlane_b32 s99, v255, 4
	v_readlane_b32 s100, v255, 17
	s_nop 3
	s_lshl_b32 s101, s100, 18
	s_add_u32 s98, s98, s101
	s_addc_u32 s99, s99, 0
	v_lshlrev_b32_e32 v232, 4, v158
	v_mov_b32_e32 v233, 0
	v_lshl_add_u64 v[232:233], s[98:99], 0, v[232:233]
	s_lshl_b32 s101, s100, 17
	s_add_u32 s98, s80, s101
	s_addc_u32 s99, s81, 0
	s_add_u32 s98, s98, 0x34000000
	s_addc_u32 s99, s99, 0
	v_lshlrev_b32_e32 v234, 3, v158
	v_mov_b32_e32 v235, 0
	v_lshl_add_u64 v[234:235], s[98:99], 0, v[234:235]
	v_mov_b32_e32 v236, 0x800
	v_mov_b32_e32 v237, 0
	v_mov_b32_e32 v238, 0x400
	v_mov_b32_e32 v239, 0
	v_mov_b32_e32 v244, 0x100
	v_mov_b32_e32 v245, 0
	v_mov_b32_e32 v202, 0x1000
	v_mov_b32_e32 v203, 0
	v_mov_b32_e32 v195, 0
	global_load_dwordx4 v[224:227], v[232:233], off nt
	global_load_dwordx4 v[228:231], v[232:233], off offset:1024 nt
	v_lshl_add_u64 v[232:233], v[232:233], 0, v[236:237]

.Lmy_tw1_done:
	s_cmpk_eq_i32 s1, 0x7f
	s_cbranch_scc1 .LBB0_421
	global_load_dwordx4 v[224:227], v[232:233], off nt
	global_load_dwordx4 v[228:231], v[232:233], off offset:1024 nt
	v_lshl_add_u64 v[232:233], v[232:233], 0, v[236:237]
	s_branch .LBB0_421

.LBB0_524:
	s_nop 0
	v_lshl_add_u64 v[10:11], s[6:7], 0, v[184:185]
	v_add_co_u32_e64 v24, s[0:1], s14, v10
	v_lshl_add_u64 v[12:13], s[12:13], 0, v[184:185]
	s_nop 0
	v_addc_co_u32_e64 v25, s[0:1], 0, v11, s[0:1]
	v_add_co_u32_e32 v26, vcc, 0x2c000000, v12
	v_add_co_u32_e64 v16, s[0:1], s15, v12
	s_nop 0
	v_addc_co_u32_e32 v27, vcc, 0, v13, vcc
	v_addc_co_u32_e64 v17, s[0:1], 0, v13, s[0:1]
	v_add_co_u32_e64 v18, s[0:1], s16, v12
	v_add_co_u32_e32 v28, vcc, 0x30000000, v12
	s_nop 0
	v_addc_co_u32_e64 v19, s[0:1], 0, v13, s[0:1]
	v_addc_co_u32_e32 v29, vcc, 0, v13, vcc
	v_add_co_u32_e64 v20, s[0:1], s17, v12
	v_add_co_u32_e32 v12, vcc, 0x28000000, v12
	s_nop 0
	v_addc_co_u32_e64 v21, s[0:1], 0, v13, s[0:1]
	v_addc_co_u32_e32 v13, vcc, 0, v13, vcc
	global_load_dwordx4 v[68:71], v[26:27], off nt
	global_load_dwordx4 v[72:75], v[28:29], off nt
	global_load_dwordx4 v[76:79], v[12:13], off nt
	global_load_dwordx4 v[80:83], v[26:27], off offset:1024 nt
	global_load_dwordx4 v[84:87], v[28:29], off offset:1024 nt
	global_load_dwordx4 v[88:91], v[12:13], off offset:1024 nt
	global_load_dwordx4 v[92:95], v[26:27], off offset:2048 nt
	global_load_dwordx4 v[96:99], v[28:29], off offset:2048 nt
	global_load_dwordx4 v[100:103], v[12:13], off offset:2048 nt
	global_load_dwordx4 v[104:107], v[26:27], off offset:3072 nt
	global_load_dwordx4 v[108:111], v[28:29], off offset:3072 nt
	global_load_dwordx4 v[112:115], v[12:13], off offset:3072 nt
	global_load_dwordx4 v[116:119], v[16:17], off nt
	global_load_dwordx4 v[120:123], v[18:19], off nt
	global_load_dwordx4 v[124:127], v[20:21], off nt
	global_load_dwordx4 v[128:131], v[16:17], off offset:1024 nt
	global_load_dwordx4 v[132:135], v[18:19], off offset:1024 nt
	global_load_dwordx4 v[136:139], v[20:21], off offset:1024 nt
	global_load_dwordx4 v[140:143], v[16:17], off offset:2048 nt
	global_load_dwordx4 v[144:147], v[18:19], off offset:2048 nt
	global_load_dwordx4 v[148:151], v[20:21], off offset:2048 nt
	global_load_dwordx4 v[152:155], v[16:17], off offset:3072 nt
	global_load_dwordx4 v[156:159], v[18:19], off offset:3072 nt
	global_load_dwordx4 v[160:163], v[20:21], off offset:3072 nt
	v_add_co_u32_e64 v22, s[0:1], s18, v10
	s_add_u32 s6, s6, 0x4000
	s_nop 0
	v_addc_co_u32_e64 v23, s[0:1], 0, v11, s[0:1]
	v_add_co_u32_e64 v14, s[0:1], s19, v10
	s_addc_u32 s7, s7, 0
	s_nop 0
	v_addc_co_u32_e64 v15, s[0:1], 0, v11, s[0:1]
	s_add_u32 s12, s12, 0x2000
	s_addc_u32 s13, s13, 0
	s_add_i32 s2, s2, -8
	s_cmp_eq_u32 s2, 0
	s_waitcnt vmcnt(21)
	v_mov_b32_e32 v36, v68
	v_mov_b32_e32 v37, v69
	v_mov_b32_e32 v38, v70
	v_mov_b32_e32 v39, v71
	v_mov_b32_e32 v40, v72
	v_mov_b32_e32 v41, v73
	v_mov_b32_e32 v42, v74
	v_mov_b32_e32 v43, v75
	v_mov_b32_e32 v44, v76
	v_mov_b32_e32 v45, v77
	v_mov_b32_e32 v46, v78
	v_mov_b32_e32 v47, v79
	v_lshlrev_b32_e32 v48, 16, v39
	v_and_b32_e32 v49, 0xffff0000, v39
	v_lshlrev_b32_e32 v50, 16, v38
	v_and_b32_e32 v51, 0xffff0000, v38
	v_lshlrev_b32_e32 v38, 16, v37
	v_and_b32_e32 v39, 0xffff0000, v37
	v_lshlrev_b32_e32 v52, 16, v36
	v_and_b32_e32 v53, 0xffff0000, v36
	v_lshlrev_b32_e32 v36, 16, v43
	v_and_b32_e32 v37, 0xffff0000, v43
	v_lshlrev_b32_e32 v54, 16, v42
	v_and_b32_e32 v55, 0xffff0000, v42
	v_lshlrev_b32_e32 v42, 16, v41
	v_and_b32_e32 v43, 0xffff0000, v41
	v_lshlrev_b32_e32 v56, 16, v40
	v_and_b32_e32 v57, 0xffff0000, v40
	v_pk_add_f32 v[36:37], v[48:49], v[36:37]
	v_lshlrev_b32_e32 v40, 16, v47
	v_and_b32_e32 v41, 0xffff0000, v47
	v_pk_add_f32 v[48:49], v[50:51], v[54:55]
	v_lshlrev_b32_e32 v50, 16, v46
	v_and_b32_e32 v51, 0xffff0000, v46
	v_pk_add_f32 v[38:39], v[38:39], v[42:43]
	v_and_b32_e32 v43, 0xffff0000, v45
	v_pk_add_f32 v[46:47], v[52:53], v[56:57]
	v_lshlrev_b32_e32 v42, 16, v45
	v_and_b32_e32 v53, 0xffff0000, v44
	v_mul_f32_e32 v60, 0xbfb8aa3b, v50
	v_mul_f32_e32 v63, 0xbfb8aa3b, v43
	v_pk_mul_f32 v[58:59], v[46:47], v[46:47]
	v_lshlrev_b32_e32 v52, 16, v44
	v_pk_mul_f32 v[56:57], v[38:39], v[38:39]
	v_mul_f32_e32 v62, 0xbfb8aa3b, v42
	v_mul_f32_e32 v65, 0xbfb8aa3b, v53
	v_exp_f32_e32 v60, v60
	v_exp_f32_e32 v63, v63
	v_add_f32_e32 v58, v58, v59
	v_mul_f32_e32 v61, 0xbfb8aa3b, v51
	v_mul_f32_e32 v64, 0xbfb8aa3b, v52
	v_mul_f32_e32 v66, 0xbfb8aa3b, v40
	v_exp_f32_e32 v62, v62
	v_exp_f32_e32 v65, v65
	v_add_f32_e32 v56, v56, v58
	v_pk_mul_f32 v[54:55], v[48:49], v[48:49]
	v_exp_f32_e32 v61, v61
	v_exp_f32_e32 v64, v64
	v_exp_f32_e32 v59, v66
	v_add_f32_e32 v56, v57, v56
	v_add_f32_e32 v54, v54, v56
	v_pk_mul_f32 v[44:45], v[36:37], v[36:37]
	v_add_f32_e32 v56, 1.0, v60
	v_add_f32_e32 v60, 1.0, v63
	v_add_f32_e32 v63, v55, v54
	v_add_f32_e32 v58, 1.0, v62
	v_add_f32_e32 v62, 1.0, v65
	v_add_f32_e32 v44, v44, v63
	v_add_f32_e32 v57, 1.0, v61
	v_add_f32_e32 v61, 1.0, v64
	v_add_f32_e32 v64, 1.0, v59
	v_rcp_f32_e32 v59, v62
	v_add_f32_e32 v62, v45, v44
	ds_bpermute_b32 v63, v31, v62
	v_rcp_f32_e32 v54, v56
	v_rcp_f32_e32 v55, v57
	v_rcp_f32_e32 v56, v58
	v_rcp_f32_e32 v58, v61
	v_mul_f32_e32 v67, 0xbfb8aa3b, v41
	v_pk_mul_f32 v[44:45], v[54:55], v[50:51]
	v_exp_f32_e32 v66, v67
	v_pk_mul_f32 v[50:51], v[58:59], v[52:53]
	s_waitcnt lgkmcnt(0)
	v_add_f32_e32 v52, v62, v63
	ds_bpermute_b32 v53, v32, v52
	v_add_f32_e32 v65, 1.0, v66
	v_rcp_f32_e32 v57, v60
	v_rcp_f32_e32 v60, v64
	v_rcp_f32_e32 v61, v65
	s_waitcnt lgkmcnt(0)
	v_add_f32_e32 v52, v52, v53
	ds_bpermute_b32 v53, v33, v52
	v_pk_mul_f32 v[42:43], v[56:57], v[42:43]
	v_pk_mul_f32 v[40:41], v[60:61], v[40:41]
	s_waitcnt lgkmcnt(0)
	v_add_f32_e32 v52, v52, v53
	ds_bpermute_b32 v53, v34, v52
	s_waitcnt lgkmcnt(0)
	v_add_f32_e32 v52, v52, v53
	v_fmamk_f32 v52, v52, 0x3c000000, v35
	v_mul_f32_e32 v53, 0x4b800000, v52
	v_cmp_gt_f32_e32 vcc, s3, v52
	s_nop 1
	v_cndmask_b32_e32 v52, v52, v53, vcc
	v_rsq_f32_e32 v52, v52
	s_nop 0
	v_mul_f32_e32 v53, 0x45800000, v52
	v_cndmask_b32_e32 v52, v52, v53, vcc
	v_pk_mul_f32 v[46:47], v[46:47], v[52:53] op_sel_hi:[1,0]
	v_pk_mul_f32 v[38:39], v[38:39], v[52:53] op_sel_hi:[1,0]
	v_pk_mul_f32 v[48:49], v[48:49], v[52:53] op_sel_hi:[1,0]
	v_pk_mul_f32 v[36:37], v[36:37], v[52:53] op_sel_hi:[1,0]
	v_pk_mul_f32 v[46:47], v[2:3], v[46:47]
	v_pk_mul_f32 v[38:39], v[4:5], v[38:39]
	v_pk_mul_f32 v[48:49], v[6:7], v[48:49]
	v_pk_mul_f32 v[36:37], v[8:9], v[36:37]
	v_pk_mul_f32 v[46:47], v[50:51], v[46:47]
	v_pk_mul_f32 v[38:39], v[42:43], v[38:39]
	v_pk_mul_f32 v[42:43], v[44:45], v[48:49]
	v_pk_mul_f32 v[40:41], v[40:41], v[36:37]
	v_cvt_pk_bf16_f32 v36, v46, v47
	v_cvt_pk_bf16_f32 v37, v38, v39
	v_cvt_pk_bf16_f32 v38, v42, v43
	v_cvt_pk_bf16_f32 v39, v40, v41
	global_store_dwordx4 v[10:11], v[36:39], off offset:1024
	s_nop 1
	s_waitcnt vmcnt(19)
	v_mov_b32_e32 v36, v80
	v_mov_b32_e32 v37, v81
	v_mov_b32_e32 v38, v82
	v_mov_b32_e32 v39, v83
	v_mov_b32_e32 v40, v84
	v_mov_b32_e32 v41, v85
	v_mov_b32_e32 v42, v86
	v_mov_b32_e32 v43, v87
	v_mov_b32_e32 v44, v88
	v_mov_b32_e32 v45, v89
	v_mov_b32_e32 v46, v90
	v_mov_b32_e32 v47, v91
	s_nop 0
	v_lshlrev_b32_e32 v48, 16, v39
	v_and_b32_e32 v49, 0xffff0000, v39
	v_lshlrev_b32_e32 v50, 16, v43
	v_and_b32_e32 v51, 0xffff0000, v43
	v_lshlrev_b32_e32 v52, 16, v47
	v_and_b32_e32 v53, 0xffff0000, v47
	v_lshlrev_b32_e32 v54, 16, v38
	v_and_b32_e32 v55, 0xffff0000, v38
	v_lshlrev_b32_e32 v38, 16, v42
	v_and_b32_e32 v39, 0xffff0000, v42
	v_lshlrev_b32_e32 v42, 16, v46
	v_and_b32_e32 v43, 0xffff0000, v46
	v_lshlrev_b32_e32 v46, 16, v37
	v_and_b32_e32 v47, 0xffff0000, v37
	v_lshlrev_b32_e32 v56, 16, v41
	v_and_b32_e32 v57, 0xffff0000, v41
	v_lshlrev_b32_e32 v58, 16, v45
	v_and_b32_e32 v59, 0xffff0000, v45
	v_lshlrev_b32_e32 v60, 16, v36
	v_and_b32_e32 v61, 0xffff0000, v36
	v_lshlrev_b32_e32 v36, 16, v40
	v_and_b32_e32 v37, 0xffff0000, v40
	v_pk_add_f32 v[38:39], v[54:55], v[38:39]
	v_mul_f32_e32 v54, 0xbfb8aa3b, v42
	v_mul_f32_e32 v55, 0xbfb8aa3b, v43
	v_pk_add_f32 v[46:47], v[46:47], v[56:57]
	v_mul_f32_e32 v56, 0xbfb8aa3b, v58
	v_mul_f32_e32 v57, 0xbfb8aa3b, v59
	v_pk_add_f32 v[36:37], v[60:61], v[36:37]
	v_exp_f32_e32 v64, v54
	v_exp_f32_e32 v65, v55
	v_exp_f32_e32 v66, v56
	v_exp_f32_e32 v67, v57
	v_pk_mul_f32 v[56:57], v[36:37], v[36:37]
	v_mul_f32_e32 v62, 0xbfb8aa3b, v52
	v_pk_mul_f32 v[54:55], v[46:47], v[46:47]
	v_add_f32_e32 v56, v56, v57
	v_mul_f32_e32 v63, 0xbfb8aa3b, v53
	v_exp_f32_e32 v62, v62
	v_add_f32_e32 v54, v54, v56
	v_lshlrev_b32_e32 v40, 16, v44
	v_and_b32_e32 v41, 0xffff0000, v44
	v_pk_add_f32 v[44:45], v[48:49], v[50:51]
	v_pk_mul_f32 v[50:51], v[38:39], v[38:39]
	v_exp_f32_e32 v63, v63
	v_add_f32_e32 v54, v55, v54
	v_add_f32_e32 v55, 1.0, v64
	v_add_f32_e32 v56, 1.0, v65
	v_add_f32_e32 v57, 1.0, v66
	v_add_f32_e32 v64, 1.0, v67
	v_add_f32_e32 v50, v50, v54
	v_pk_mul_f32 v[48:49], v[44:45], v[44:45]
	v_rcp_f32_e32 v54, v55
	v_rcp_f32_e32 v55, v56
	v_rcp_f32_e32 v56, v57
	v_rcp_f32_e32 v57, v64
	v_add_f32_e32 v64, v51, v50
	v_add_f32_e32 v62, 1.0, v62
	v_add_f32_e32 v48, v48, v64
	v_add_f32_e32 v63, 1.0, v63
	v_rcp_f32_e32 v50, v62
	v_add_f32_e32 v62, v49, v48
	v_rcp_f32_e32 v51, v63
	ds_bpermute_b32 v63, v31, v62
	v_mul_f32_e32 v60, 0xbfb8aa3b, v40
	v_mul_f32_e32 v61, 0xbfb8aa3b, v41
	v_pk_mul_f32 v[50:51], v[50:51], v[52:53]
	v_exp_f32_e32 v60, v60
	s_waitcnt lgkmcnt(0)
	v_add_f32_e32 v52, v62, v63
	ds_bpermute_b32 v53, v32, v52
	v_exp_f32_e32 v61, v61
	v_add_f32_e32 v60, 1.0, v60
	v_rcp_f32_e32 v60, v60
	v_pk_mul_f32 v[42:43], v[54:55], v[42:43]
	s_waitcnt lgkmcnt(0)
	v_add_f32_e32 v52, v52, v53
	ds_bpermute_b32 v53, v33, v52
	v_add_f32_e32 v61, 1.0, v61
	v_rcp_f32_e32 v61, v61
	v_pk_mul_f32 v[48:49], v[56:57], v[58:59]
	s_waitcnt lgkmcnt(0)
	v_add_f32_e32 v52, v52, v53
	ds_bpermute_b32 v53, v34, v52
	v_pk_mul_f32 v[40:41], v[60:61], v[40:41]
	s_waitcnt lgkmcnt(0)
	v_add_f32_e32 v52, v52, v53
	v_fmamk_f32 v52, v52, 0x3c000000, v35
	v_mul_f32_e32 v53, 0x4b800000, v52
	v_cmp_gt_f32_e32 vcc, s3, v52
	s_nop 1
	v_cndmask_b32_e32 v52, v52, v53, vcc
	v_rsq_f32_e32 v52, v52
	s_nop 0
	v_mul_f32_e32 v53, 0x45800000, v52
	v_cndmask_b32_e32 v52, v52, v53, vcc
	v_pk_mul_f32 v[36:37], v[36:37], v[52:53] op_sel_hi:[1,0]
	v_pk_mul_f32 v[46:47], v[46:47], v[52:53] op_sel_hi:[1,0]
	v_pk_mul_f32 v[38:39], v[38:39], v[52:53] op_sel_hi:[1,0]
	v_pk_mul_f32 v[44:45], v[44:45], v[52:53] op_sel_hi:[1,0]
	v_pk_mul_f32 v[36:37], v[2:3], v[36:37]
	v_pk_mul_f32 v[46:47], v[4:5], v[46:47]
	v_pk_mul_f32 v[38:39], v[6:7], v[38:39]
	v_pk_mul_f32 v[44:45], v[8:9], v[44:45]
	v_pk_mul_f32 v[36:37], v[40:41], v[36:37]
	v_pk_mul_f32 v[40:41], v[48:49], v[46:47]
	v_pk_mul_f32 v[38:39], v[42:43], v[38:39]
	v_pk_mul_f32 v[42:43], v[50:51], v[44:45]
	v_cvt_pk_bf16_f32 v36, v36, v37
	v_cvt_pk_bf16_f32 v37, v40, v41
	v_cvt_pk_bf16_f32 v38, v38, v39
	v_cvt_pk_bf16_f32 v39, v42, v43
	global_store_dwordx4 v[10:11], v[36:39], off offset:3072
	s_nop 1
	s_waitcnt vmcnt(17)
	v_mov_b32_e32 v36, v92
	v_mov_b32_e32 v37, v93
	v_mov_b32_e32 v38, v94
	v_mov_b32_e32 v39, v95
	v_mov_b32_e32 v40, v96
	v_mov_b32_e32 v41, v97
	v_mov_b32_e32 v42, v98
	v_mov_b32_e32 v43, v99
	v_mov_b32_e32 v44, v100
	v_mov_b32_e32 v45, v101
	v_mov_b32_e32 v46, v102
	v_mov_b32_e32 v47, v103
	s_nop 0
	v_lshlrev_b32_e32 v10, 16, v39
	v_and_b32_e32 v11, 0xffff0000, v39
	v_lshlrev_b32_e32 v48, 16, v43
	v_and_b32_e32 v49, 0xffff0000, v43
	v_lshlrev_b32_e32 v50, 16, v47
	v_and_b32_e32 v51, 0xffff0000, v47
	v_lshlrev_b32_e32 v52, 16, v38
	v_and_b32_e32 v53, 0xffff0000, v38
	v_lshlrev_b32_e32 v38, 16, v42
	v_and_b32_e32 v39, 0xffff0000, v42
	v_lshlrev_b32_e32 v42, 16, v46
	v_and_b32_e32 v43, 0xffff0000, v46
	v_lshlrev_b32_e32 v46, 16, v37
	v_and_b32_e32 v47, 0xffff0000, v37
	v_lshlrev_b32_e32 v54, 16, v41
	v_and_b32_e32 v55, 0xffff0000, v41
	v_lshlrev_b32_e32 v56, 16, v45
	v_and_b32_e32 v57, 0xffff0000, v45
	v_lshlrev_b32_e32 v58, 16, v36
	v_and_b32_e32 v59, 0xffff0000, v36
	v_lshlrev_b32_e32 v36, 16, v40
	v_and_b32_e32 v37, 0xffff0000, v40
	v_lshlrev_b32_e32 v40, 16, v44
	v_and_b32_e32 v41, 0xffff0000, v44
	v_pk_add_f32 v[38:39], v[52:53], v[38:39]
	v_mul_f32_e32 v52, 0xbfb8aa3b, v42
	v_mul_f32_e32 v53, 0xbfb8aa3b, v43
	v_pk_add_f32 v[44:45], v[46:47], v[54:55]
	v_mul_f32_e32 v54, 0xbfb8aa3b, v56
	v_mul_f32_e32 v55, 0xbfb8aa3b, v57
	v_pk_add_f32 v[36:37], v[58:59], v[36:37]
	v_exp_f32_e32 v62, v52
	v_exp_f32_e32 v63, v53
	v_exp_f32_e32 v64, v54
	v_exp_f32_e32 v65, v55
	v_pk_mul_f32 v[54:55], v[36:37], v[36:37]
	v_mul_f32_e32 v60, 0xbfb8aa3b, v50
	v_pk_mul_f32 v[52:53], v[44:45], v[44:45]
	v_add_f32_e32 v54, v54, v55
	v_mul_f32_e32 v61, 0xbfb8aa3b, v51
	v_exp_f32_e32 v60, v60
	v_add_f32_e32 v52, v52, v54
	v_pk_add_f32 v[10:11], v[10:11], v[48:49]
	v_pk_mul_f32 v[48:49], v[38:39], v[38:39]
	v_exp_f32_e32 v61, v61
	v_add_f32_e32 v52, v53, v52
	v_add_f32_e32 v53, 1.0, v62
	v_add_f32_e32 v54, 1.0, v63
	v_add_f32_e32 v55, 1.0, v64
	v_add_f32_e32 v62, 1.0, v65
	v_add_f32_e32 v48, v48, v52
	v_pk_mul_f32 v[46:47], v[10:11], v[10:11]
	v_rcp_f32_e32 v52, v53
	v_rcp_f32_e32 v53, v54
	v_rcp_f32_e32 v54, v55
	v_rcp_f32_e32 v55, v62
	v_add_f32_e32 v62, v49, v48
	v_add_f32_e32 v60, 1.0, v60
	v_add_f32_e32 v46, v46, v62
	v_add_f32_e32 v61, 1.0, v61
	v_rcp_f32_e32 v48, v60
	v_add_f32_e32 v60, v47, v46
	v_rcp_f32_e32 v49, v61
	ds_bpermute_b32 v61, v31, v60
	v_mul_f32_e32 v58, 0xbfb8aa3b, v40
	v_mul_f32_e32 v59, 0xbfb8aa3b, v41
	v_pk_mul_f32 v[48:49], v[48:49], v[50:51]
	v_exp_f32_e32 v58, v58
	s_waitcnt lgkmcnt(0)
	v_add_f32_e32 v50, v60, v61
	ds_bpermute_b32 v51, v32, v50
	v_exp_f32_e32 v59, v59
	v_add_f32_e32 v58, 1.0, v58
	v_rcp_f32_e32 v58, v58
	v_pk_mul_f32 v[42:43], v[52:53], v[42:43]
	s_waitcnt lgkmcnt(0)
	v_add_f32_e32 v50, v50, v51
	ds_bpermute_b32 v51, v33, v50
	v_add_f32_e32 v59, 1.0, v59
	v_rcp_f32_e32 v59, v59
	v_pk_mul_f32 v[46:47], v[54:55], v[56:57]
	s_waitcnt lgkmcnt(0)
	v_add_f32_e32 v50, v50, v51
	ds_bpermute_b32 v51, v34, v50
	v_pk_mul_f32 v[40:41], v[58:59], v[40:41]
	s_waitcnt lgkmcnt(0)
	v_add_f32_e32 v50, v50, v51
	v_fmamk_f32 v50, v50, 0x3c000000, v35
	v_mul_f32_e32 v51, 0x4b800000, v50
	v_cmp_gt_f32_e32 vcc, s3, v50
	s_nop 1
	v_cndmask_b32_e32 v50, v50, v51, vcc
	v_rsq_f32_e32 v50, v50
	s_nop 0
	v_mul_f32_e32 v51, 0x45800000, v50
	v_cndmask_b32_e32 v50, v50, v51, vcc
	v_pk_mul_f32 v[36:37], v[36:37], v[50:51] op_sel_hi:[1,0]
	v_pk_mul_f32 v[44:45], v[44:45], v[50:51] op_sel_hi:[1,0]
	v_pk_mul_f32 v[38:39], v[38:39], v[50:51] op_sel_hi:[1,0]
	v_pk_mul_f32 v[10:11], v[10:11], v[50:51] op_sel_hi:[1,0]
	v_pk_mul_f32 v[36:37], v[2:3], v[36:37]
	v_pk_mul_f32 v[44:45], v[4:5], v[44:45]
	v_pk_mul_f32 v[38:39], v[6:7], v[38:39]
	v_pk_mul_f32 v[10:11], v[8:9], v[10:11]
	v_pk_mul_f32 v[36:37], v[40:41], v[36:37]
	v_pk_mul_f32 v[40:41], v[46:47], v[44:45]
	v_pk_mul_f32 v[38:39], v[42:43], v[38:39]
	v_pk_mul_f32 v[10:11], v[48:49], v[10:11]
	v_cvt_pk_bf16_f32 v36, v36, v37
	v_cvt_pk_bf16_f32 v37, v40, v41
	v_cvt_pk_bf16_f32 v38, v38, v39
	v_cvt_pk_bf16_f32 v39, v10, v11
	global_store_dwordx4 v[24:25], v[36:39], off offset:1024
	s_nop 1
	s_waitcnt vmcnt(15)
	v_mov_b32_e32 v36, v104
	v_mov_b32_e32 v37, v105
	v_mov_b32_e32 v38, v106
	v_mov_b32_e32 v39, v107
	v_mov_b32_e32 v40, v108
	v_mov_b32_e32 v41, v109
	v_mov_b32_e32 v42, v110
	v_mov_b32_e32 v43, v111
	v_mov_b32_e32 v44, v112
	v_mov_b32_e32 v45, v113
	v_mov_b32_e32 v46, v114
	v_mov_b32_e32 v47, v115
	s_nop 0
	v_lshlrev_b32_e32 v10, 16, v39
	v_and_b32_e32 v11, 0xffff0000, v39
	v_lshlrev_b32_e32 v12, 16, v43
	v_and_b32_e32 v13, 0xffff0000, v43
	v_lshlrev_b32_e32 v26, 16, v47
	v_and_b32_e32 v27, 0xffff0000, v47
	v_lshlrev_b32_e32 v28, 16, v38
	v_and_b32_e32 v29, 0xffff0000, v38
	v_lshlrev_b32_e32 v38, 16, v42
	v_and_b32_e32 v39, 0xffff0000, v42
	v_lshlrev_b32_e32 v42, 16, v46
	v_and_b32_e32 v43, 0xffff0000, v46
	v_lshlrev_b32_e32 v46, 16, v37
	v_and_b32_e32 v47, 0xffff0000, v37
	v_lshlrev_b32_e32 v48, 16, v41
	v_and_b32_e32 v49, 0xffff0000, v41
	v_lshlrev_b32_e32 v50, 16, v45
	v_and_b32_e32 v51, 0xffff0000, v45
	v_lshlrev_b32_e32 v52, 16, v36
	v_and_b32_e32 v53, 0xffff0000, v36
	v_lshlrev_b32_e32 v36, 16, v40
	v_and_b32_e32 v37, 0xffff0000, v40
	v_pk_add_f32 v[10:11], v[10:11], v[12:13]
	v_pk_add_f32 v[12:13], v[28:29], v[38:39]
	v_mul_f32_e32 v54, 0xbfb8aa3b, v42
	v_mul_f32_e32 v55, 0xbfb8aa3b, v43
	v_pk_add_f32 v[28:29], v[46:47], v[48:49]
	v_mul_f32_e32 v48, 0xbfb8aa3b, v50
	v_mul_f32_e32 v49, 0xbfb8aa3b, v51
	v_pk_add_f32 v[36:37], v[52:53], v[36:37]
	v_exp_f32_e32 v54, v54
	v_exp_f32_e32 v55, v55
	v_exp_f32_e32 v58, v48
	v_exp_f32_e32 v59, v49
	v_pk_mul_f32 v[48:49], v[36:37], v[36:37]
	v_pk_mul_f32 v[46:47], v[28:29], v[28:29]
	v_add_f32_e32 v48, v48, v49
	v_mul_f32_e32 v56, 0xbfb8aa3b, v26
	v_add_f32_e32 v46, v46, v48
	v_lshlrev_b32_e32 v40, 16, v44
	v_and_b32_e32 v41, 0xffff0000, v44
	v_mul_f32_e32 v57, 0xbfb8aa3b, v27
	v_pk_mul_f32 v[44:45], v[12:13], v[12:13]
	v_exp_f32_e32 v56, v56
	v_add_f32_e32 v46, v47, v46
	v_exp_f32_e32 v57, v57
	v_add_f32_e32 v47, 1.0, v54
	v_add_f32_e32 v48, 1.0, v55
	v_add_f32_e32 v49, 1.0, v58
	v_add_f32_e32 v54, 1.0, v59
	v_add_f32_e32 v44, v44, v46
	v_pk_mul_f32 v[38:39], v[10:11], v[10:11]
	v_rcp_f32_e32 v46, v47
	v_rcp_f32_e32 v47, v48
	v_rcp_f32_e32 v48, v49
	v_rcp_f32_e32 v49, v54
	v_add_f32_e32 v54, v45, v44
	v_add_f32_e32 v38, v38, v54
	v_add_f32_e32 v55, 1.0, v56
	v_add_f32_e32 v54, v39, v38
	v_add_f32_e32 v56, 1.0, v57
	v_rcp_f32_e32 v44, v55
	ds_bpermute_b32 v55, v31, v54
	v_rcp_f32_e32 v45, v56
	v_mul_f32_e32 v52, 0xbfb8aa3b, v40
	v_mul_f32_e32 v53, 0xbfb8aa3b, v41
	v_exp_f32_e32 v52, v52
	v_pk_mul_f32 v[26:27], v[44:45], v[26:27]
	s_waitcnt lgkmcnt(0)
	v_add_f32_e32 v44, v54, v55
	ds_bpermute_b32 v45, v32, v44
	v_exp_f32_e32 v53, v53
	v_add_f32_e32 v52, 1.0, v52
	v_rcp_f32_e32 v52, v52
	v_pk_mul_f32 v[38:39], v[46:47], v[42:43]
	s_waitcnt lgkmcnt(0)
	v_add_f32_e32 v44, v44, v45
	ds_bpermute_b32 v45, v33, v44
	v_add_f32_e32 v53, 1.0, v53
	v_rcp_f32_e32 v53, v53
	v_pk_mul_f32 v[42:43], v[48:49], v[50:51]
	s_waitcnt lgkmcnt(0)
	v_add_f32_e32 v44, v44, v45
	ds_bpermute_b32 v45, v34, v44
	v_pk_mul_f32 v[40:41], v[52:53], v[40:41]
	s_waitcnt lgkmcnt(0)
	v_add_f32_e32 v44, v44, v45
	v_fmamk_f32 v44, v44, 0x3c000000, v35
	v_mul_f32_e32 v45, 0x4b800000, v44
	v_cmp_gt_f32_e32 vcc, s3, v44
	s_nop 1
	v_cndmask_b32_e32 v44, v44, v45, vcc
	v_rsq_f32_e32 v44, v44
	s_nop 0
	v_mul_f32_e32 v45, 0x45800000, v44
	v_cndmask_b32_e32 v44, v44, v45, vcc
	v_pk_mul_f32 v[36:37], v[36:37], v[44:45] op_sel_hi:[1,0]
	v_pk_mul_f32 v[28:29], v[28:29], v[44:45] op_sel_hi:[1,0]
	v_pk_mul_f32 v[12:13], v[12:13], v[44:45] op_sel_hi:[1,0]
	v_pk_mul_f32 v[10:11], v[10:11], v[44:45] op_sel_hi:[1,0]
	v_pk_mul_f32 v[36:37], v[2:3], v[36:37]
	v_pk_mul_f32 v[28:29], v[4:5], v[28:29]
	v_pk_mul_f32 v[12:13], v[6:7], v[12:13]
	v_pk_mul_f32 v[10:11], v[8:9], v[10:11]
	v_pk_mul_f32 v[36:37], v[40:41], v[36:37]
	v_pk_mul_f32 v[28:29], v[42:43], v[28:29]
	v_pk_mul_f32 v[12:13], v[38:39], v[12:13]
	v_pk_mul_f32 v[26:27], v[26:27], v[10:11]
	v_cvt_pk_bf16_f32 v10, v36, v37
	v_cvt_pk_bf16_f32 v11, v28, v29
	v_cvt_pk_bf16_f32 v12, v12, v13
	v_cvt_pk_bf16_f32 v13, v26, v27
	global_store_dwordx4 v[24:25], v[10:13], off offset:3072
	s_nop 1
	s_waitcnt vmcnt(13)
	v_mov_b32_e32 v10, v116
	v_mov_b32_e32 v11, v117
	v_mov_b32_e32 v12, v118
	v_mov_b32_e32 v13, v119
	v_mov_b32_e32 v24, v120
	v_mov_b32_e32 v25, v121
	v_mov_b32_e32 v26, v122
	v_mov_b32_e32 v27, v123
	v_mov_b32_e32 v36, v124
	v_mov_b32_e32 v37, v125
	v_mov_b32_e32 v38, v126
	v_mov_b32_e32 v39, v127
	s_nop 0
	v_lshlrev_b32_e32 v28, 16, v13
	v_and_b32_e32 v29, 0xffff0000, v13
	v_lshlrev_b32_e32 v40, 16, v27
	v_and_b32_e32 v41, 0xffff0000, v27
	v_lshlrev_b32_e32 v42, 16, v39
	v_and_b32_e32 v43, 0xffff0000, v39
	v_lshlrev_b32_e32 v44, 16, v12
	v_and_b32_e32 v45, 0xffff0000, v12
	v_lshlrev_b32_e32 v12, 16, v26
	v_and_b32_e32 v13, 0xffff0000, v26
	v_lshlrev_b32_e32 v26, 16, v38
	v_and_b32_e32 v27, 0xffff0000, v38
	v_lshlrev_b32_e32 v38, 16, v11
	v_and_b32_e32 v39, 0xffff0000, v11
	v_lshlrev_b32_e32 v46, 16, v25
	v_and_b32_e32 v47, 0xffff0000, v25
	v_lshlrev_b32_e32 v48, 16, v37
	v_and_b32_e32 v49, 0xffff0000, v37
	v_lshlrev_b32_e32 v50, 16, v10
	v_and_b32_e32 v51, 0xffff0000, v10
	v_lshlrev_b32_e32 v10, 16, v24
	v_and_b32_e32 v11, 0xffff0000, v24
	v_lshlrev_b32_e32 v24, 16, v36
	v_and_b32_e32 v25, 0xffff0000, v36
	v_pk_add_f32 v[12:13], v[44:45], v[12:13]
	v_mul_f32_e32 v44, 0xbfb8aa3b, v26
	v_mul_f32_e32 v45, 0xbfb8aa3b, v27
	v_pk_add_f32 v[36:37], v[38:39], v[46:47]
	v_mul_f32_e32 v46, 0xbfb8aa3b, v48
	v_mul_f32_e32 v47, 0xbfb8aa3b, v49
	v_pk_add_f32 v[10:11], v[50:51], v[10:11]
	v_exp_f32_e32 v54, v44
	v_exp_f32_e32 v55, v45
	v_exp_f32_e32 v56, v46
	v_exp_f32_e32 v57, v47
	v_pk_mul_f32 v[46:47], v[10:11], v[10:11]
	v_mul_f32_e32 v52, 0xbfb8aa3b, v42
	v_pk_mul_f32 v[44:45], v[36:37], v[36:37]
	v_add_f32_e32 v46, v46, v47
	v_mul_f32_e32 v53, 0xbfb8aa3b, v43
	v_exp_f32_e32 v52, v52
	v_add_f32_e32 v44, v44, v46
	v_pk_add_f32 v[28:29], v[28:29], v[40:41]
	v_pk_mul_f32 v[40:41], v[12:13], v[12:13]
	v_exp_f32_e32 v53, v53
	v_add_f32_e32 v44, v45, v44
	v_add_f32_e32 v45, 1.0, v54
	v_add_f32_e32 v46, 1.0, v55
	v_add_f32_e32 v47, 1.0, v56
	v_add_f32_e32 v54, 1.0, v57
	v_add_f32_e32 v40, v40, v44
	v_pk_mul_f32 v[38:39], v[28:29], v[28:29]
	v_rcp_f32_e32 v44, v45
	v_rcp_f32_e32 v45, v46
	v_rcp_f32_e32 v46, v47
	v_rcp_f32_e32 v47, v54
	v_add_f32_e32 v54, v41, v40
	v_add_f32_e32 v52, 1.0, v52
	v_add_f32_e32 v38, v38, v54
	v_add_f32_e32 v53, 1.0, v53
	v_rcp_f32_e32 v40, v52
	v_add_f32_e32 v52, v39, v38
	v_rcp_f32_e32 v41, v53
	ds_bpermute_b32 v53, v31, v52
	v_mul_f32_e32 v50, 0xbfb8aa3b, v24
	v_mul_f32_e32 v51, 0xbfb8aa3b, v25
	v_pk_mul_f32 v[40:41], v[40:41], v[42:43]
	v_exp_f32_e32 v50, v50
	s_waitcnt lgkmcnt(0)
	v_add_f32_e32 v42, v52, v53
	ds_bpermute_b32 v43, v32, v42
	v_exp_f32_e32 v51, v51
	v_add_f32_e32 v50, 1.0, v50
	v_rcp_f32_e32 v50, v50
	v_pk_mul_f32 v[26:27], v[44:45], v[26:27]
	s_waitcnt lgkmcnt(0)
	v_add_f32_e32 v42, v42, v43
	ds_bpermute_b32 v43, v33, v42
	v_add_f32_e32 v51, 1.0, v51
	v_rcp_f32_e32 v51, v51
	v_pk_mul_f32 v[38:39], v[46:47], v[48:49]
	s_waitcnt lgkmcnt(0)
	v_add_f32_e32 v42, v42, v43
	ds_bpermute_b32 v43, v34, v42
	v_pk_mul_f32 v[24:25], v[50:51], v[24:25]
	s_waitcnt lgkmcnt(0)
	v_add_f32_e32 v42, v42, v43
	v_fmamk_f32 v42, v42, 0x3c000000, v35
	v_mul_f32_e32 v43, 0x4b800000, v42
	v_cmp_gt_f32_e32 vcc, s3, v42
	s_nop 1
	v_cndmask_b32_e32 v42, v42, v43, vcc
	v_rsq_f32_e32 v42, v42
	s_nop 0
	v_mul_f32_e32 v43, 0x45800000, v42
	v_cndmask_b32_e32 v42, v42, v43, vcc
	v_pk_mul_f32 v[10:11], v[10:11], v[42:43] op_sel_hi:[1,0]
	v_pk_mul_f32 v[36:37], v[36:37], v[42:43] op_sel_hi:[1,0]
	v_pk_mul_f32 v[12:13], v[12:13], v[42:43] op_sel_hi:[1,0]
	v_pk_mul_f32 v[28:29], v[28:29], v[42:43] op_sel_hi:[1,0]
	v_pk_mul_f32 v[10:11], v[2:3], v[10:11]
	v_pk_mul_f32 v[36:37], v[4:5], v[36:37]
	v_pk_mul_f32 v[12:13], v[6:7], v[12:13]
	v_pk_mul_f32 v[28:29], v[8:9], v[28:29]
	v_pk_mul_f32 v[10:11], v[24:25], v[10:11]
	v_pk_mul_f32 v[24:25], v[38:39], v[36:37]
	v_pk_mul_f32 v[12:13], v[26:27], v[12:13]
	v_pk_mul_f32 v[26:27], v[40:41], v[28:29]
	v_cvt_pk_bf16_f32 v10, v10, v11
	v_cvt_pk_bf16_f32 v11, v24, v25
	v_cvt_pk_bf16_f32 v12, v12, v13
	v_cvt_pk_bf16_f32 v13, v26, v27
	global_store_dwordx4 v[22:23], v[10:13], off offset:1024
	s_nop 1
	s_waitcnt vmcnt(11)
	v_mov_b32_e32 v10, v128
	v_mov_b32_e32 v11, v129
	v_mov_b32_e32 v12, v130
	v_mov_b32_e32 v13, v131
	v_mov_b32_e32 v24, v132
	v_mov_b32_e32 v25, v133
	v_mov_b32_e32 v26, v134
	v_mov_b32_e32 v27, v135
	v_mov_b32_e32 v36, v136
	v_mov_b32_e32 v37, v137
	v_mov_b32_e32 v38, v138
	v_mov_b32_e32 v39, v139
	s_nop 0
	v_lshlrev_b32_e32 v28, 16, v13
	v_and_b32_e32 v29, 0xffff0000, v13
	v_lshlrev_b32_e32 v40, 16, v27
	v_and_b32_e32 v41, 0xffff0000, v27
	v_lshlrev_b32_e32 v42, 16, v39
	v_and_b32_e32 v43, 0xffff0000, v39
	v_lshlrev_b32_e32 v44, 16, v12
	v_and_b32_e32 v45, 0xffff0000, v12
	v_lshlrev_b32_e32 v12, 16, v26
	v_and_b32_e32 v13, 0xffff0000, v26
	v_lshlrev_b32_e32 v26, 16, v38
	v_and_b32_e32 v27, 0xffff0000, v38
	v_lshlrev_b32_e32 v38, 16, v11
	v_and_b32_e32 v39, 0xffff0000, v11
	v_lshlrev_b32_e32 v46, 16, v25
	v_and_b32_e32 v47, 0xffff0000, v25
	v_lshlrev_b32_e32 v48, 16, v37
	v_and_b32_e32 v49, 0xffff0000, v37
	v_lshlrev_b32_e32 v50, 16, v10
	v_and_b32_e32 v51, 0xffff0000, v10
	v_lshlrev_b32_e32 v10, 16, v24
	v_and_b32_e32 v11, 0xffff0000, v24
	v_lshlrev_b32_e32 v24, 16, v36
	v_and_b32_e32 v25, 0xffff0000, v36
	v_pk_add_f32 v[12:13], v[44:45], v[12:13]
	v_mul_f32_e32 v44, 0xbfb8aa3b, v26
	v_mul_f32_e32 v45, 0xbfb8aa3b, v27
	v_pk_add_f32 v[36:37], v[38:39], v[46:47]
	v_mul_f32_e32 v46, 0xbfb8aa3b, v48
	v_mul_f32_e32 v47, 0xbfb8aa3b, v49
	v_pk_add_f32 v[10:11], v[50:51], v[10:11]
	v_exp_f32_e32 v54, v44
	v_exp_f32_e32 v55, v45
	v_exp_f32_e32 v56, v46
	v_exp_f32_e32 v57, v47
	v_pk_mul_f32 v[46:47], v[10:11], v[10:11]
	v_mul_f32_e32 v52, 0xbfb8aa3b, v42
	v_pk_mul_f32 v[44:45], v[36:37], v[36:37]
	v_add_f32_e32 v46, v46, v47
	v_mul_f32_e32 v53, 0xbfb8aa3b, v43
	v_exp_f32_e32 v52, v52
	v_add_f32_e32 v44, v44, v46
	v_pk_add_f32 v[28:29], v[28:29], v[40:41]
	v_pk_mul_f32 v[40:41], v[12:13], v[12:13]
	v_exp_f32_e32 v53, v53
	v_add_f32_e32 v44, v45, v44
	v_add_f32_e32 v45, 1.0, v54
	v_add_f32_e32 v46, 1.0, v55
	v_add_f32_e32 v47, 1.0, v56
	v_add_f32_e32 v54, 1.0, v57
	v_add_f32_e32 v40, v40, v44
	v_pk_mul_f32 v[38:39], v[28:29], v[28:29]
	v_rcp_f32_e32 v44, v45
	v_rcp_f32_e32 v45, v46
	v_rcp_f32_e32 v46, v47
	v_rcp_f32_e32 v47, v54
	v_add_f32_e32 v54, v41, v40
	v_add_f32_e32 v52, 1.0, v52
	v_add_f32_e32 v38, v38, v54
	v_add_f32_e32 v53, 1.0, v53
	v_rcp_f32_e32 v40, v52
	v_add_f32_e32 v52, v39, v38
	v_rcp_f32_e32 v41, v53
	ds_bpermute_b32 v53, v31, v52
	v_mul_f32_e32 v50, 0xbfb8aa3b, v24
	v_mul_f32_e32 v51, 0xbfb8aa3b, v25
	v_pk_mul_f32 v[40:41], v[40:41], v[42:43]
	v_exp_f32_e32 v50, v50
	s_waitcnt lgkmcnt(0)
	v_add_f32_e32 v42, v52, v53
	ds_bpermute_b32 v43, v32, v42
	v_exp_f32_e32 v51, v51
	v_add_f32_e32 v50, 1.0, v50
	v_rcp_f32_e32 v50, v50
	v_pk_mul_f32 v[26:27], v[44:45], v[26:27]
	s_waitcnt lgkmcnt(0)
	v_add_f32_e32 v42, v42, v43
	ds_bpermute_b32 v43, v33, v42
	v_add_f32_e32 v51, 1.0, v51
	v_rcp_f32_e32 v51, v51
	v_pk_mul_f32 v[38:39], v[46:47], v[48:49]
	s_waitcnt lgkmcnt(0)
	v_add_f32_e32 v42, v42, v43
	ds_bpermute_b32 v43, v34, v42
	v_pk_mul_f32 v[24:25], v[50:51], v[24:25]
	s_waitcnt lgkmcnt(0)
	v_add_f32_e32 v42, v42, v43
	v_fmamk_f32 v42, v42, 0x3c000000, v35
	v_mul_f32_e32 v43, 0x4b800000, v42
	v_cmp_gt_f32_e32 vcc, s3, v42
	s_nop 1
	v_cndmask_b32_e32 v42, v42, v43, vcc
	v_rsq_f32_e32 v42, v42
	s_nop 0
	v_mul_f32_e32 v43, 0x45800000, v42
	v_cndmask_b32_e32 v42, v42, v43, vcc
	v_pk_mul_f32 v[10:11], v[10:11], v[42:43] op_sel_hi:[1,0]
	v_pk_mul_f32 v[36:37], v[36:37], v[42:43] op_sel_hi:[1,0]
	v_pk_mul_f32 v[12:13], v[12:13], v[42:43] op_sel_hi:[1,0]
	v_pk_mul_f32 v[28:29], v[28:29], v[42:43] op_sel_hi:[1,0]
	v_pk_mul_f32 v[10:11], v[2:3], v[10:11]
	v_pk_mul_f32 v[36:37], v[4:5], v[36:37]
	v_pk_mul_f32 v[12:13], v[6:7], v[12:13]
	v_pk_mul_f32 v[28:29], v[8:9], v[28:29]
	v_pk_mul_f32 v[10:11], v[24:25], v[10:11]
	v_pk_mul_f32 v[24:25], v[38:39], v[36:37]
	v_pk_mul_f32 v[12:13], v[26:27], v[12:13]
	v_pk_mul_f32 v[26:27], v[40:41], v[28:29]
	v_cvt_pk_bf16_f32 v10, v10, v11
	v_cvt_pk_bf16_f32 v11, v24, v25
	v_cvt_pk_bf16_f32 v12, v12, v13
	v_cvt_pk_bf16_f32 v13, v26, v27
	global_store_dwordx4 v[22:23], v[10:13], off offset:3072
	s_nop 1
	s_waitcnt vmcnt(9)
	v_mov_b32_e32 v10, v140
	v_mov_b32_e32 v11, v141
	v_mov_b32_e32 v12, v142
	v_mov_b32_e32 v13, v143
	v_mov_b32_e32 v22, v144
	v_mov_b32_e32 v23, v145
	v_mov_b32_e32 v24, v146
	v_mov_b32_e32 v25, v147
	v_mov_b32_e32 v26, v148
	v_mov_b32_e32 v27, v149
	v_mov_b32_e32 v28, v150
	v_mov_b32_e32 v29, v151
	s_nop 0
	v_lshlrev_b32_e32 v36, 16, v13
	v_and_b32_e32 v37, 0xffff0000, v13
	v_lshlrev_b32_e32 v38, 16, v25
	v_and_b32_e32 v39, 0xffff0000, v25
	v_lshlrev_b32_e32 v40, 16, v29
	v_and_b32_e32 v41, 0xffff0000, v29
	v_lshlrev_b32_e32 v42, 16, v12
	v_and_b32_e32 v43, 0xffff0000, v12
	v_lshlrev_b32_e32 v12, 16, v24
	v_and_b32_e32 v13, 0xffff0000, v24
	v_lshlrev_b32_e32 v24, 16, v28
	v_and_b32_e32 v25, 0xffff0000, v28
	v_lshlrev_b32_e32 v28, 16, v11
	v_and_b32_e32 v29, 0xffff0000, v11
	v_lshlrev_b32_e32 v44, 16, v23
	v_and_b32_e32 v45, 0xffff0000, v23
	v_lshlrev_b32_e32 v46, 16, v27
	v_and_b32_e32 v47, 0xffff0000, v27
	v_lshlrev_b32_e32 v48, 16, v10
	v_and_b32_e32 v49, 0xffff0000, v10
	v_lshlrev_b32_e32 v10, 16, v22
	v_and_b32_e32 v11, 0xffff0000, v22
	v_pk_add_f32 v[12:13], v[42:43], v[12:13]
	v_mul_f32_e32 v42, 0xbfb8aa3b, v24
	v_mul_f32_e32 v43, 0xbfb8aa3b, v25
	v_pk_add_f32 v[28:29], v[28:29], v[44:45]
	v_mul_f32_e32 v44, 0xbfb8aa3b, v46
	v_mul_f32_e32 v45, 0xbfb8aa3b, v47
	v_pk_add_f32 v[10:11], v[48:49], v[10:11]
	v_exp_f32_e32 v52, v42
	v_exp_f32_e32 v53, v43
	v_exp_f32_e32 v54, v44
	v_exp_f32_e32 v55, v45
	v_pk_mul_f32 v[44:45], v[10:11], v[10:11]
	v_mul_f32_e32 v50, 0xbfb8aa3b, v40
	v_pk_mul_f32 v[42:43], v[28:29], v[28:29]
	v_add_f32_e32 v44, v44, v45
	v_mul_f32_e32 v51, 0xbfb8aa3b, v41
	v_exp_f32_e32 v50, v50
	v_add_f32_e32 v42, v42, v44
	v_lshlrev_b32_e32 v22, 16, v26
	v_and_b32_e32 v23, 0xffff0000, v26
	v_pk_add_f32 v[26:27], v[36:37], v[38:39]
	v_pk_mul_f32 v[38:39], v[12:13], v[12:13]
	v_exp_f32_e32 v51, v51
	v_add_f32_e32 v42, v43, v42
	v_add_f32_e32 v43, 1.0, v52
	v_add_f32_e32 v44, 1.0, v53
	v_add_f32_e32 v45, 1.0, v54
	v_add_f32_e32 v52, 1.0, v55
	v_add_f32_e32 v38, v38, v42
	v_pk_mul_f32 v[36:37], v[26:27], v[26:27]
	v_rcp_f32_e32 v42, v43
	v_rcp_f32_e32 v43, v44
	v_rcp_f32_e32 v44, v45
	v_rcp_f32_e32 v45, v52
	v_add_f32_e32 v52, v39, v38
	v_add_f32_e32 v50, 1.0, v50
	v_add_f32_e32 v36, v36, v52
	v_add_f32_e32 v51, 1.0, v51
	v_rcp_f32_e32 v38, v50
	v_add_f32_e32 v50, v37, v36
	v_rcp_f32_e32 v39, v51
	ds_bpermute_b32 v51, v31, v50
	v_mul_f32_e32 v48, 0xbfb8aa3b, v22
	v_mul_f32_e32 v49, 0xbfb8aa3b, v23
	v_pk_mul_f32 v[38:39], v[38:39], v[40:41]
	v_exp_f32_e32 v48, v48
	s_waitcnt lgkmcnt(0)
	v_add_f32_e32 v40, v50, v51
	ds_bpermute_b32 v41, v32, v40
	v_exp_f32_e32 v49, v49
	v_add_f32_e32 v48, 1.0, v48
	v_rcp_f32_e32 v48, v48
	v_pk_mul_f32 v[24:25], v[42:43], v[24:25]
	s_waitcnt lgkmcnt(0)
	v_add_f32_e32 v40, v40, v41
	ds_bpermute_b32 v41, v33, v40
	v_add_f32_e32 v49, 1.0, v49
	v_rcp_f32_e32 v49, v49
	v_pk_mul_f32 v[36:37], v[44:45], v[46:47]
	s_waitcnt lgkmcnt(0)
	v_add_f32_e32 v40, v40, v41
	ds_bpermute_b32 v41, v34, v40
	v_pk_mul_f32 v[22:23], v[48:49], v[22:23]
	s_waitcnt lgkmcnt(0)
	v_add_f32_e32 v40, v40, v41
	v_fmamk_f32 v40, v40, 0x3c000000, v35
	v_mul_f32_e32 v41, 0x4b800000, v40
	v_cmp_gt_f32_e32 vcc, s3, v40
	s_nop 1
	v_cndmask_b32_e32 v40, v40, v41, vcc
	v_rsq_f32_e32 v40, v40
	s_nop 0
	v_mul_f32_e32 v41, 0x45800000, v40
	v_cndmask_b32_e32 v40, v40, v41, vcc
	v_pk_mul_f32 v[10:11], v[10:11], v[40:41] op_sel_hi:[1,0]
	v_pk_mul_f32 v[28:29], v[28:29], v[40:41] op_sel_hi:[1,0]
	v_pk_mul_f32 v[12:13], v[12:13], v[40:41] op_sel_hi:[1,0]
	v_pk_mul_f32 v[26:27], v[26:27], v[40:41] op_sel_hi:[1,0]
	v_pk_mul_f32 v[10:11], v[2:3], v[10:11]
	v_pk_mul_f32 v[28:29], v[4:5], v[28:29]
	v_pk_mul_f32 v[12:13], v[6:7], v[12:13]
	v_pk_mul_f32 v[26:27], v[8:9], v[26:27]
	v_pk_mul_f32 v[10:11], v[22:23], v[10:11]
	v_pk_mul_f32 v[22:23], v[36:37], v[28:29]
	v_pk_mul_f32 v[12:13], v[24:25], v[12:13]
	v_pk_mul_f32 v[24:25], v[38:39], v[26:27]
	v_cvt_pk_bf16_f32 v10, v10, v11
	v_cvt_pk_bf16_f32 v11, v22, v23
	v_cvt_pk_bf16_f32 v12, v12, v13
	v_cvt_pk_bf16_f32 v13, v24, v25
	global_store_dwordx4 v[14:15], v[10:13], off offset:1024
	s_nop 1
	s_waitcnt vmcnt(7)
	v_mov_b32_e32 v10, v152
	v_mov_b32_e32 v11, v153
	v_mov_b32_e32 v12, v154
	v_mov_b32_e32 v13, v155
	v_mov_b32_e32 v22, v156
	v_mov_b32_e32 v23, v157
	v_mov_b32_e32 v24, v158
	v_mov_b32_e32 v25, v159
	v_mov_b32_e32 v26, v160
	v_mov_b32_e32 v27, v161
	v_mov_b32_e32 v28, v162
	v_mov_b32_e32 v29, v163
	s_nop 0
	v_lshlrev_b32_e32 v16, 16, v13
	v_and_b32_e32 v17, 0xffff0000, v13
	v_lshlrev_b32_e32 v18, 16, v25
	v_and_b32_e32 v19, 0xffff0000, v25
	v_lshlrev_b32_e32 v20, 16, v29
	v_and_b32_e32 v21, 0xffff0000, v29
	v_lshlrev_b32_e32 v36, 16, v12
	v_and_b32_e32 v37, 0xffff0000, v12
	v_lshlrev_b32_e32 v12, 16, v24
	v_and_b32_e32 v13, 0xffff0000, v24
	v_lshlrev_b32_e32 v24, 16, v28
	v_and_b32_e32 v25, 0xffff0000, v28
	v_lshlrev_b32_e32 v28, 16, v11
	v_and_b32_e32 v29, 0xffff0000, v11
	v_lshlrev_b32_e32 v38, 16, v23
	v_and_b32_e32 v39, 0xffff0000, v23
	v_lshlrev_b32_e32 v40, 16, v27
	v_and_b32_e32 v41, 0xffff0000, v27
	v_lshlrev_b32_e32 v42, 16, v10
	v_and_b32_e32 v43, 0xffff0000, v10
	v_lshlrev_b32_e32 v10, 16, v22
	v_and_b32_e32 v11, 0xffff0000, v22
	v_pk_add_f32 v[16:17], v[16:17], v[18:19]
	v_pk_add_f32 v[12:13], v[36:37], v[12:13]
	v_mul_f32_e32 v36, 0xbfb8aa3b, v24
	v_mul_f32_e32 v37, 0xbfb8aa3b, v25
	v_pk_add_f32 v[18:19], v[28:29], v[38:39]
	v_mul_f32_e32 v38, 0xbfb8aa3b, v40
	v_mul_f32_e32 v39, 0xbfb8aa3b, v41
	v_pk_add_f32 v[10:11], v[42:43], v[10:11]
	v_exp_f32_e32 v46, v36
	v_exp_f32_e32 v47, v37
	v_exp_f32_e32 v48, v38
	v_exp_f32_e32 v49, v39
	v_pk_mul_f32 v[38:39], v[10:11], v[10:11]
	v_mul_f32_e32 v44, 0xbfb8aa3b, v20
	v_pk_mul_f32 v[36:37], v[18:19], v[18:19]
	v_add_f32_e32 v38, v38, v39
	v_mul_f32_e32 v45, 0xbfb8aa3b, v21
	v_exp_f32_e32 v44, v44
	v_add_f32_e32 v36, v36, v38
	v_pk_mul_f32 v[28:29], v[12:13], v[12:13]
	v_exp_f32_e32 v45, v45
	v_add_f32_e32 v36, v37, v36
	v_add_f32_e32 v37, 1.0, v46
	v_add_f32_e32 v38, 1.0, v47
	v_add_f32_e32 v39, 1.0, v48
	v_add_f32_e32 v46, 1.0, v49
	v_add_f32_e32 v28, v28, v36
	v_lshlrev_b32_e32 v22, 16, v26
	v_and_b32_e32 v23, 0xffff0000, v26
	v_pk_mul_f32 v[26:27], v[16:17], v[16:17]
	v_rcp_f32_e32 v36, v37
	v_rcp_f32_e32 v37, v38
	v_rcp_f32_e32 v38, v39
	v_rcp_f32_e32 v39, v46
	v_add_f32_e32 v46, v29, v28
	v_add_f32_e32 v44, 1.0, v44
	v_add_f32_e32 v26, v26, v46
	v_add_f32_e32 v45, 1.0, v45
	v_rcp_f32_e32 v28, v44
	v_add_f32_e32 v44, v27, v26
	v_rcp_f32_e32 v29, v45
	ds_bpermute_b32 v45, v31, v44
	v_mul_f32_e32 v42, 0xbfb8aa3b, v22
	v_mul_f32_e32 v43, 0xbfb8aa3b, v23
	v_pk_mul_f32 v[20:21], v[28:29], v[20:21]
	v_exp_f32_e32 v42, v42
	s_waitcnt lgkmcnt(0)
	v_add_f32_e32 v28, v44, v45
	ds_bpermute_b32 v29, v32, v28
	v_exp_f32_e32 v43, v43
	v_add_f32_e32 v42, 1.0, v42
	v_rcp_f32_e32 v42, v42
	v_pk_mul_f32 v[24:25], v[36:37], v[24:25]
	s_waitcnt lgkmcnt(0)
	v_add_f32_e32 v28, v28, v29
	ds_bpermute_b32 v29, v33, v28
	v_add_f32_e32 v43, 1.0, v43
	v_rcp_f32_e32 v43, v43
	v_pk_mul_f32 v[26:27], v[38:39], v[40:41]
	s_waitcnt lgkmcnt(0)
	v_add_f32_e32 v28, v28, v29
	ds_bpermute_b32 v29, v34, v28
	v_pk_mul_f32 v[22:23], v[42:43], v[22:23]
	s_waitcnt lgkmcnt(0)
	v_add_f32_e32 v28, v28, v29
	v_fmamk_f32 v28, v28, 0x3c000000, v35
	v_mul_f32_e32 v29, 0x4b800000, v28
	v_cmp_gt_f32_e32 vcc, s3, v28
	s_nop 1
	v_cndmask_b32_e32 v28, v28, v29, vcc
	v_rsq_f32_e32 v28, v28
	s_nop 0
	v_mul_f32_e32 v29, 0x45800000, v28
	v_cndmask_b32_e32 v28, v28, v29, vcc
	v_pk_mul_f32 v[10:11], v[10:11], v[28:29] op_sel_hi:[1,0]
	v_pk_mul_f32 v[18:19], v[18:19], v[28:29] op_sel_hi:[1,0]
	v_pk_mul_f32 v[12:13], v[12:13], v[28:29] op_sel_hi:[1,0]
	v_pk_mul_f32 v[16:17], v[16:17], v[28:29] op_sel_hi:[1,0]
	v_pk_mul_f32 v[10:11], v[2:3], v[10:11]
	v_pk_mul_f32 v[18:19], v[4:5], v[18:19]
	v_pk_mul_f32 v[12:13], v[6:7], v[12:13]
	v_pk_mul_f32 v[16:17], v[8:9], v[16:17]
	v_pk_mul_f32 v[10:11], v[22:23], v[10:11]
	v_pk_mul_f32 v[18:19], v[26:27], v[18:19]
	v_pk_mul_f32 v[12:13], v[24:25], v[12:13]
	v_pk_mul_f32 v[16:17], v[20:21], v[16:17]
	v_cvt_pk_bf16_f32 v10, v10, v11
	v_cvt_pk_bf16_f32 v11, v18, v19
	v_cvt_pk_bf16_f32 v12, v12, v13
	v_cvt_pk_bf16_f32 v13, v16, v17
	global_store_dwordx4 v[14:15], v[10:13], off offset:3072
	s_cbranch_scc0 .LBB0_524
	v_mov_b32_e32 v8, v0
	s_barrier
	s_mov_b32 s3, 0x1fffe0
	v_lshlrev_b32_e32 v2, 4, v8
	v_add_u32_e32 v3, 0x2000, v2
	v_ashrrev_i32_e32 v4, 31, v3
	v_lshrrev_b32_e32 v4, 22, v4
	v_add_u32_e32 v4, v3, v4
	v_ashrrev_i32_e32 v6, 10, v4
	v_mul_i32_i24_e32 v4, 0x400, v6
	v_sub_u32_e32 v3, v3, v4
	v_lshrrev_b32_e32 v4, 4, v3
	v_bitop3_b32 v3, v4, v3, 32 bitop3:0x6c
	v_ashrrev_i32_e32 v4, 31, v3
	v_lshrrev_b32_e32 v4, 26, v4
	v_add_u32_e32 v4, v3, v4
	v_lshlrev_b32_e32 v5, 3, v6
	v_ashrrev_i32_e32 v7, 6, v4
	v_and_b32_e32 v5, -16, v5
	v_add_u32_e32 v5, v7, v5
	v_and_b32_e32 v9, 3, v7
	v_lshrrev_b32_e32 v10, 2, v5
	v_lshlrev_b32_e32 v11, 1, v5
	v_and_b32_e32 v4, 0xc0, v4
	v_and_or_b32 v9, v5, s3, v9
	v_and_b32_e32 v10, 4, v10
	v_and_b32_e32 v11, 24, v11
	v_sub_u32_e32 v3, v3, v4
	v_mov_b32_e32 v4, 1
	v_or3_b32 v10, v9, v10, v11
	v_lshlrev_b32_e32 v9, 5, v6
	v_ashrrev_i16_sdwa v3, v4, sext(v3) dst_sel:DWORD dst_unused:UNUSED_PAD src0_sel:DWORD src1_sel:BYTE_0
	v_and_b32_e32 v11, 32, v9
	v_bfe_i32 v9, v3, 0, 16
	v_add_lshl_u32 v3, v11, v9, 1
	v_lshl_add_u32 v178, v10, 11, v3
	v_lshl_add_u32 v180, v5, 11, v3
	v_bfe_i32 v3, v8, 27, 1
	v_lshrrev_b32_e32 v3, 22, v3
	v_add_u32_e32 v3, v2, v3
	v_and_b32_e32 v3, 0xfffffc00, v3
	v_sub_u32_e32 v2, v2, v3
	v_lshrrev_b32_e32 v3, 4, v2
	v_ashrrev_i32_e32 v5, 31, v8
	v_bitop3_b32 v2, v3, v2, 32 bitop3:0x6c
	v_lshrrev_b32_e32 v5, 26, v5
	v_ashrrev_i32_e32 v3, 31, v2
	v_add_u32_e32 v5, v8, v5
	v_lshrrev_b32_e32 v3, 26, v3
	v_ashrrev_i32_e32 v11, 6, v5
	v_add_u32_e32 v3, v2, v3
	v_lshlrev_b32_e32 v5, 3, v11
	v_ashrrev_i32_e32 v10, 6, v3
	v_and_b32_e32 v5, -16, v5
	v_add_u32_e32 v5, v10, v5
	v_and_b32_e32 v12, 3, v10
	v_lshrrev_b32_e32 v13, 2, v5
	v_lshlrev_b32_e32 v14, 1, v5
	v_and_b32_e32 v3, 0xc0, v3
	v_readfirstlane_b32 s2, v8
	v_and_or_b32 v12, v5, s3, v12
	v_and_b32_e32 v13, 4, v13
	v_and_b32_e32 v14, 24, v14
	v_sub_u32_e32 v2, v2, v3
	s_ashr_i32 s0, s2, 6
	v_or3_b32 v13, v12, v13, v14
	v_lshlrev_b32_e32 v12, 5, v11
	v_ashrrev_i16_sdwa v2, v4, sext(v2) dst_sel:DWORD dst_unused:UNUSED_PAD src0_sel:DWORD src1_sel:BYTE_0
	s_lshl_b32 s12, s0, 10
	v_and_b32_e32 v14, 32, v12
	v_bfe_i32 v12, v2, 0, 16
	v_add_lshl_u32 v2, v14, v12, 1
	s_add_i32 s3, s12, 0
	v_lshl_add_u32 v182, v13, 11, v2
	s_add_i32 m0, s3, 0x10000
	s_ashr_i32 s1, s2, 8
	global_load_lds_dwordx4 v182, s[88:89]
	s_add_i32 m0, s3, 0x12000
	s_add_u32 s6, s80, s8
	v_lshl_add_u32 v190, v5, 11, v2
	global_load_lds_dwordx4 v178, s[88:89]
	s_addc_u32 s7, s81, s9
	s_mov_b32 m0, s3
	s_add_i32 s20, s3, 0x2000
	global_load_lds_dwordx4 v190, s[6:7]
	s_mov_b32 m0, s20
	s_add_u32 s14, s80, 0x36940000
	global_load_lds_dwordx4 v180, s[6:7]
	s_addc_u32 s15, s81, 0
	s_add_i32 m0, s3, 0x14000
	v_mov_b32_e32 v183, 0
	global_load_lds_dwordx4 v182, s[14:15]
	s_add_i32 m0, s3, 0x16000
	v_mov_b32_e32 v191, v183
	global_load_lds_dwordx4 v178, s[14:15]
	s_add_u32 s14, s6, 0x40000
	s_addc_u32 s15, s7, 0
	s_add_i32 s21, s3, 0x4000
	s_mov_b32 m0, s21
	s_add_i32 s22, s3, 0x6000
	global_load_lds_dwordx4 v190, s[14:15]
	s_mov_b32 m0, s22
	v_mov_b32_e32 v181, v183
	global_load_lds_dwordx4 v180, s[14:15]
	s_mov_b32 s23, 0
	v_mov_b32_e32 v179, v183
	v_lshl_add_u64 v[4:5], s[6:7], 0, v[190:191]
	s_cmp_lg_u32 s1, 1
	v_lshl_add_u64 v[2:3], s[6:7], 0, v[180:181]
	s_cbranch_scc1 .LBB0_527
	s_barrier
